# as v171 but without the (now redundant) drain in front of the XCD release atomic at two barrier sites
# baseline (speedup 1.0000x reference)
.LBB0_465:
	s_or_b64 exec, exec, s[2:3]
	v_mov_b32_e32 v0, s25
	v_add_co_u32_e32 v0, vcc, 0x2000, v0
	v_mov_b32_e32 v1, s24
	s_nop 0
	v_addc_co_u32_e32 v1, vcc, 0, v1, vcc
	s_nop 0
	flat_atomic_add v[0:1], v176 offset:1024
	s_waitcnt vmcnt(0)
